# attention: s-m subtraction folded into S-MFMA accumulator init (tuples of -m), removes 32 VALU per KV tile
# speedup vs baseline: 1.1703x; 1.0092x over previous
; DEV void attn_item(const Params& p, int item, char* smem) {
;     ...
;   float mrun[2] = {-1e30f, -1e30f}, lrun[2] = {0.f, 0.f};
;   u32x4 rk0, rk1, rv0;
;   const int k0row = tid / 12, k0cc = tid - k0row * 12;
;   const int k1id = 256 + (tid & 127), k1row = k1id / 12, k1cc = k1id - k1row * 12;
;   const bool has_k1 = tid < 128;
;   const int vrow = tid >> 2, vcc = tid & 3;
;   const int ntile = nkeys >> 5;
;   __syncthreads();
;   rk0 = *(const u32x4*)(Kb + (size_t)k0row * 96 + k0cc * 8);
;   rk1 = *(const u32x4*)(Kb + (size_t)k1row * 96 + k1cc * 8);
;   rv0 = *(const u32x4*)(Vb + (size_t)vrow * 8448 + vcc * 8);
;   *(u32x4*)(Ks + k0row * ASTR + k0cc * 8) = rk0;
;   if (has_k1) *(u32x4*)(Ks + k1row * ASTR + k1cc * 8) = rk1;
;   *(uint2*)(Vs + vrow * VSTR + vcc * 8) = make_uint2(rv0[0], rv0[1]);
;   *(uint2*)(Vs + vrow * VSTR + vcc * 8 + 4) = make_uint2(rv0[2], rv0[3]);
;   __syncthreads();
;   if (ntile > 1) {
;     rk0 = *(const u32x4*)(Kb + (size_t)(32 + k0row) * 96 + k0cc * 8);
;     rk1 = *(const u32x4*)(Kb + (size_t)(32 + k1row) * 96 + k1cc * 8);
;     rv0 = *(const u32x4*)(Vb + (size_t)vrow * 8448 + 32 + vcc * 8);
;   }
.LBB0_751:
	s_or_b64 exec, exec, s[14:15]
	s_movk_i32 s15, 0x58
	v_mul_lo_u32 v15, v12, s15
	v_lshl_add_u32 v186, v14, 1, v15
	v_add_u32_e32 v14, 0x3400, v186
	s_waitcnt vmcnt(0)
	ds_write2_b64 v14, v[2:3], v[4:5] offset1:1
	v_lshlrev_b64 v[2:3], 1, v[174:175]
	v_lshl_add_u64 v[4:5], v[8:9], 0, v[2:3]
	s_movk_i32 s14, 0x1000
	v_add_co_u32_e32 v4, vcc, s14, v4
	s_waitcnt lgkmcnt(0)
	s_nop 0
	v_addc_co_u32_e32 v5, vcc, 0, v5, vcc
	s_barrier
	global_load_dwordx4 v[160:163], v[6:7], off offset:64
	global_load_dwordx4 v[164:167], v[4:5], off offset:2048
	v_add_u32_e32 v6, 32, v11
	v_mov_b64_e32 v[4:5], s[12:13]
	s_movk_i32 s14, 0xc0
	v_mad_i64_i32 v[4:5], s[12:13], v6, s14, v[4:5]
	v_lshlrev_b64 v[6:7], 1, v[176:177]
	v_lshl_add_u64 v[4:5], v[4:5], 0, v[6:7]
	global_load_dwordx4 v[168:171], v[4:5], off
	v_mad_i64_i32 v[4:5], s[12:13], v11, s14, 0
	s_movk_i32 s12, 0x4200
	s_nop 0
	v_mad_i64_i32 v[8:9], s[12:13], v12, s12, 0
	v_and_b32_e32 v173, 31, v172
	s_movk_i32 s13, 0xd0
	v_mad_u32_u24 v187, v173, s13, v0
	v_lshlrev_b32_e32 v0, 3, v10
	v_mad_u32_u24 v177, v173, s15, v0
	v_and_b32_e32 v0, 3, v172
	v_lshl_add_u64 v[8:9], s[10:11], 0, v[8:9]
	v_lshlrev_b32_e32 v0, 4, v0
	v_lshl_add_u64 v[8:9], v[8:9], 0, v[0:1]
	s_mov_b32 s10, 0x15555556
	v_lshl_add_u64 v[178:179], s[0:1], 0, v[8:9]
	v_mul_hi_u32 v0, v13, s10
	v_mov_b64_e32 v[8:9], s[8:9]
	v_mad_u64_u32 v[8:9], s[10:11], v0, s14, v[8:9]
	v_lshl_add_u64 v[2:3], v[8:9], 0, v[2:3]
	v_lshl_add_u64 v[180:181], s[2:3], 0, v[2:3]
	v_lshl_add_u64 v[2:3], s[8:9], 0, v[4:5]
	v_lshl_add_u64 v[2:3], v[2:3], 0, v[6:7]
	v_mov_b32_e32 v14, v1
	v_mov_b32_e32 v15, v1
	v_lshlrev_b32_e32 v189, 2, v10
	v_lshl_add_u64 v[182:183], s[2:3], 0, v[2:3]
	v_mov_b32_e32 v0, v1
	v_mov_b32_e32 v2, v1
	v_mov_b32_e32 v3, v1
	v_mov_b32_e32 v4, v1
	v_mov_b32_e32 v5, v1
	v_mov_b32_e32 v6, v1
	v_mov_b32_e32 v7, v1
	v_mov_b32_e32 v8, v1
	v_mov_b32_e32 v9, v1
	v_mov_b32_e32 v10, v1
	v_mov_b32_e32 v11, v1
	v_mov_b32_e32 v12, v1
	v_mov_b32_e32 v13, v1
	v_mov_b64_e32 v[62:63], v[14:15]
	v_mov_b64_e32 v[30:31], v[14:15]
	v_mov_b64_e32 v[78:79], v[14:15]
	v_mov_b64_e32 v[46:47], v[14:15]
	s_mov_b32 s12, 0
	v_mul_u32_u24_e32 v190, 0x58, v173
	s_add_i32 s13, s31, 1
	v_mov_b32_e32 v184, 0
	v_mov_b32_e32 v175, 0xf149f2ca
	v_mov_b64_e32 v[60:61], v[12:13]
	v_mov_b64_e32 v[58:59], v[10:11]
	v_mov_b64_e32 v[56:57], v[8:9]
	v_mov_b64_e32 v[54:55], v[6:7]
	v_mov_b64_e32 v[52:53], v[4:5]
	v_mov_b64_e32 v[50:51], v[2:3]
	v_mov_b64_e32 v[48:49], v[0:1]
	v_mov_b64_e32 v[28:29], v[12:13]
	v_mov_b64_e32 v[26:27], v[10:11]
	v_mov_b64_e32 v[24:25], v[8:9]
	v_mov_b64_e32 v[22:23], v[6:7]
	v_mov_b64_e32 v[20:21], v[4:5]
	v_mov_b64_e32 v[18:19], v[2:3]
	v_mov_b64_e32 v[16:17], v[0:1]
	v_mov_b64_e32 v[76:77], v[12:13]
	v_mov_b64_e32 v[74:75], v[10:11]
	v_mov_b64_e32 v[72:73], v[8:9]
	v_mov_b64_e32 v[70:71], v[6:7]
	v_mov_b64_e32 v[68:69], v[4:5]
	v_mov_b64_e32 v[66:67], v[2:3]
	v_mov_b64_e32 v[64:65], v[0:1]
	v_mov_b64_e32 v[44:45], v[12:13]
	v_mov_b64_e32 v[42:43], v[10:11]
	v_mov_b64_e32 v[40:41], v[8:9]
	v_mov_b64_e32 v[38:39], v[6:7]
	v_mov_b64_e32 v[36:37], v[4:5]
	v_mov_b64_e32 v[34:35], v[2:3]
	v_mov_b64_e32 v[32:33], v[0:1]
	v_mov_b32_e32 v185, 0
	v_mov_b32_e32 v175, 0
	v_mov_b32_e32 v14, 0
	v_mov_b32_e32 v212, 0xf149f2ca
	v_mov_b32_e32 v213, 0xf149f2ca
	v_mov_b32_e32 v196, 0
	v_mov_b32_e32 v197, 0
	v_mov_b32_e32 v198, 0
	v_mov_b32_e32 v199, 0
	v_mov_b32_e32 v200, 0
	v_mov_b32_e32 v201, 0
	v_mov_b32_e32 v202, 0
	v_mov_b32_e32 v203, 0
	v_mov_b32_e32 v204, 0
	v_mov_b32_e32 v205, 0
	v_mov_b32_e32 v206, 0
	v_mov_b32_e32 v207, 0
	v_mov_b32_e32 v208, 0
	v_mov_b32_e32 v209, 0
	v_mov_b32_e32 v210, 0
	v_mov_b32_e32 v211, 0
	v_mov_b32_e32 v220, 0
	v_mov_b32_e32 v221, 0
	v_mov_b32_e32 v222, 0
	v_mov_b32_e32 v223, 0
	v_mov_b32_e32 v224, 0
	v_mov_b32_e32 v225, 0
	v_mov_b32_e32 v226, 0
	v_mov_b32_e32 v227, 0
	v_mov_b32_e32 v228, 0
	v_mov_b32_e32 v229, 0
	v_mov_b32_e32 v230, 0
	v_mov_b32_e32 v231, 0
	v_mov_b32_e32 v232, 0
	v_mov_b32_e32 v233, 0
	v_mov_b32_e32 v234, 0
	v_mov_b32_e32 v235, 0
	s_branch .LBB0_753

; DEV unsigned pack2(float a, float b) { f32x2 v = {a, b}; return __builtin_bit_cast(unsigned, __builtin_convertvector(v, bf2_t)); }
; DEV f32x16 mfma32(bf16x8 a, bf16x8 b, f32x16 c) { return __builtin_amdgcn_mfma_f32_32x32x16_bf16(a, b, c, 0, 0, 0); }
; DEV void attn_item(const Params& p, int item, char* smem) {
;     ...
;   for (int kt = 0; kt < ntile; kt++) {
;     const bf16_t* Kc = Ks + (kt & 1) * (32 * ASTR);
;     const bf16_t* Vc = Vs + (kt & 1) * (64 * VSTR);
;     f32x16 s[2];
; #pragma unroll
;     for (int jt = 0; jt < 2; jt++) {
; #pragma unroll
;       for (int r = 0; r < 16; r++) s[jt][r] = 0.f;
; #pragma unroll
;       for (int ks = 0; ks < 6; ks++) {
;         bf16x8 kf = *(const bf16x8*)(Kc + c31 * ASTR + ks * 16 + hf * 8);
;         s[jt] = mfma32(kf, qf[jt][ks], s[jt]);
;       }
;     }
; #pragma unroll
;     for (int jt = 0; jt < 2; jt++) {
;       float m0 = fmaxf(fmaxf(s[jt][0], s[jt][1]), fmaxf(s[jt][2], s[jt][3]));
;       float m1 = fmaxf(fmaxf(s[jt][4], s[jt][5]), fmaxf(s[jt][6], s[jt][7]));
;       float m2 = fmaxf(fmaxf(s[jt][8], s[jt][9]), fmaxf(s[jt][10], s[jt][11]));
;       float m3 = fmaxf(fmaxf(s[jt][12], s[jt][13]), fmaxf(s[jt][14], s[jt][15]));
;       const float mx = fmaxf(fmaxf(m0, m1), fmaxf(m2, m3));
;       if (__any(mx > mrun[jt])) {
;         const float mxa = fmaxf(mx, __shfl_xor(mx, 32));
;         const float mnew = fmaxf(mrun[jt], mxa);
;         const float alpha = __builtin_amdgcn_exp2f(mrun[jt] - mnew);
;         mrun[jt] = mnew;
;         lrun[jt] *= alpha;
; #pragma unroll
;         for (int dt = 0; dt < 2; dt++)
; #pragma unroll
;           for (int r = 0; r < 16; r++) o[dt][jt][r] *= alpha;
;       }
;       const float mcur = mrun[jt];
;       float pv[16];
; #pragma unroll
;       for (int r = 0; r < 16; r++) pv[r] = __builtin_amdgcn_exp2f(s[jt][r] - mcur);
;       lrun[jt] += (((pv[0] + pv[1]) + (pv[2] + pv[3])) + ((pv[4] + pv[5]) + (pv[6] + pv[7]))) +
;                   (((pv[8] + pv[9]) + (pv[10] + pv[11])) + ((pv[12] + pv[13]) + (pv[14] + pv[15])));
;       bf16x8 pf[2];
; #pragma unroll
;       for (int ss = 0; ss < 2; ss++) {
;         uint4 u; u.x = pack2(pv[8 * ss + 0], pv[8 * ss + 1]); u.y = pack2(pv[8 * ss + 2], pv[8 * ss + 3]);
;         u.z = pack2(pv[8 * ss + 4], pv[8 * ss + 5]); u.w = pack2(pv[8 * ss + 6], pv[8 * ss + 7]);
;         pf[ss] = __builtin_bit_cast(bf16x8, u);
;       }
.LBB0_753:
	s_and_b32 s11, s12, 1
	s_mul_i32 s10, s11, 0x1a00
	v_add_u32_e32 v0, s10, v187
	ds_read_b128 v[2:5], v0
	ds_read_b128 v[6:9], v0 offset:32
	ds_read_b128 v[10:13], v0 offset:64
	ds_read_b128 v[240:243], v0 offset:96
	ds_read_b128 v[244:247], v0 offset:128
	ds_read_b128 v[236:239], v0 offset:160
	s_waitcnt lgkmcnt(5)
	v_mfma_f32_32x32x16_bf16 v[96:111], v[2:5], v[156:159], v[196:211]
	s_waitcnt lgkmcnt(4)
	v_mfma_f32_32x32x16_bf16 v[96:111], v[6:9], v[152:155], v[96:111]
	v_mfma_f32_32x32x16_bf16 v[80:95], v[2:5], v[132:135], v[220:235]
	s_waitcnt lgkmcnt(3)
	v_mfma_f32_32x32x16_bf16 v[96:111], v[10:13], v[148:151], v[96:111]
	v_mfma_f32_32x32x16_bf16 v[80:95], v[6:9], v[128:131], v[80:95]
	s_waitcnt lgkmcnt(2)
	v_mfma_f32_32x32x16_bf16 v[96:111], v[240:243], v[144:147], v[96:111]
	v_mfma_f32_32x32x16_bf16 v[80:95], v[10:13], v[112:115], v[80:95]
	s_waitcnt lgkmcnt(1)
	v_mfma_f32_32x32x16_bf16 v[96:111], v[244:247], v[140:143], v[96:111]
	v_mfma_f32_32x32x16_bf16 v[80:95], v[240:243], v[116:119], v[80:95]
	s_waitcnt lgkmcnt(0)
	v_mfma_f32_32x32x16_bf16 v[96:111], v[236:239], v[136:139], v[96:111]
	v_mfma_f32_32x32x16_bf16 v[80:95], v[244:247], v[120:123], v[80:95]
	s_nop 10
	v_max3_f32 v0, v96, v97, v98
	v_max3_f32 v2, v99, v100, v101
	v_max3_f32 v3, v102, v103, v104
	v_max3_f32 v4, v105, v106, v107
	v_mfma_f32_32x32x16_bf16 v[80:95], v[236:239], v[124:127], v[80:95]
	v_max3_f32 v5, v108, v109, v110
	v_max3_f32 v0, v0, v2, v111
	v_max3_f32 v3, v3, v4, v5
	v_max_f32_e32 v0, v0, v3
	v_cmp_gt_f32_e32 vcc, v0, v212
	s_cbranch_vccz .LBB0_755
	v_mbcnt_hi_u32_b32 v2, -1, v215
	v_and_b32_e32 v4, 64, v2
	v_xor_b32_e32 v3, 32, v2
	v_add_u32_e32 v4, 64, v4
	v_cmp_lt_i32_e32 vcc, v3, v4
	s_nop 1
	v_cndmask_b32_e32 v2, v2, v3, vcc
	v_lshlrev_b32_e32 v2, 2, v2
	ds_bpermute_b32 v2, v2, v0
	s_waitcnt lgkmcnt(0)
	v_max_f32_e32 v2, v0, v2
	v_exp_f32_e64 v0, -v2
	v_add_f32_e32 v185, v185, v2
	v_mov_b32_e32 v212, 0x41000000
	v_sub_f32_e32 v96, v96, v2
	v_sub_f32_e32 v97, v97, v2
	v_sub_f32_e32 v98, v98, v2
	v_sub_f32_e32 v99, v99, v2
	v_sub_f32_e32 v100, v100, v2
	v_sub_f32_e32 v101, v101, v2
	v_sub_f32_e32 v102, v102, v2
	v_sub_f32_e32 v103, v103, v2
	v_sub_f32_e32 v104, v104, v2
	v_sub_f32_e32 v105, v105, v2
	v_sub_f32_e32 v106, v106, v2
	v_sub_f32_e32 v107, v107, v2
	v_sub_f32_e32 v108, v108, v2
	v_sub_f32_e32 v109, v109, v2
	v_sub_f32_e32 v110, v110, v2
	v_sub_f32_e32 v111, v111, v2
	v_sub_f32_e32 v196, v196, v2
	v_sub_f32_e32 v197, v197, v2
	v_sub_f32_e32 v198, v198, v2
	v_sub_f32_e32 v199, v199, v2
	v_sub_f32_e32 v200, v200, v2
	v_sub_f32_e32 v201, v201, v2
	v_sub_f32_e32 v202, v202, v2
	v_sub_f32_e32 v203, v203, v2
	v_sub_f32_e32 v204, v204, v2
	v_sub_f32_e32 v205, v205, v2
	v_sub_f32_e32 v206, v206, v2
	v_sub_f32_e32 v207, v207, v2
	v_sub_f32_e32 v208, v208, v2
	v_sub_f32_e32 v209, v209, v2
	v_sub_f32_e32 v210, v210, v2
	v_sub_f32_e32 v211, v211, v2
	v_mul_f32_e32 v14, v14, v0
	v_pk_mul_f32 v[46:47], v[46:47], v[0:1] op_sel_hi:[1,0]
	v_pk_mul_f32 v[44:45], v[44:45], v[0:1] op_sel_hi:[1,0]
	v_pk_mul_f32 v[42:43], v[42:43], v[0:1] op_sel_hi:[1,0]
	v_pk_mul_f32 v[40:41], v[40:41], v[0:1] op_sel_hi:[1,0]
	v_pk_mul_f32 v[38:39], v[38:39], v[0:1] op_sel_hi:[1,0]
	v_pk_mul_f32 v[36:37], v[36:37], v[0:1] op_sel_hi:[1,0]
	v_pk_mul_f32 v[34:35], v[34:35], v[0:1] op_sel_hi:[1,0]
	v_pk_mul_f32 v[32:33], v[32:33], v[0:1] op_sel_hi:[1,0]
	v_pk_mul_f32 v[30:31], v[30:31], v[0:1] op_sel_hi:[1,0]
	v_pk_mul_f32 v[28:29], v[28:29], v[0:1] op_sel_hi:[1,0]
	v_pk_mul_f32 v[26:27], v[26:27], v[0:1] op_sel_hi:[1,0]
	v_pk_mul_f32 v[24:25], v[24:25], v[0:1] op_sel_hi:[1,0]
	v_pk_mul_f32 v[22:23], v[22:23], v[0:1] op_sel_hi:[1,0]
	v_pk_mul_f32 v[20:21], v[20:21], v[0:1] op_sel_hi:[1,0]
	v_pk_mul_f32 v[18:19], v[18:19], v[0:1] op_sel_hi:[1,0]
	v_pk_mul_f32 v[16:17], v[16:17], v[0:1] op_sel_hi:[1,0]
.LBB0_755:
	v_exp_f32_e32 v193, v97
	v_exp_f32_e32 v194, v98
	v_exp_f32_e32 v239, v99
	v_exp_f32_e32 v100, v100
	v_exp_f32_e32 v101, v101
	v_exp_f32_e32 v102, v102
	v_exp_f32_e32 v240, v103
	v_exp_f32_e32 v103, v104
	v_exp_f32_e32 v104, v105
	v_exp_f32_e32 v105, v106
	v_exp_f32_e32 v106, v107
	s_mulk_i32 s11, 0x1600
	v_exp_f32_e32 v107, v108
	v_exp_f32_e32 v108, v109
	v_add_u32_e32 v10, s11, v177
	v_exp_f32_e32 v109, v110
	v_add_u32_e32 v6, 0x3000, v10
	v_add_u32_e32 v15, 0x3800, v10
	v_exp_f32_e32 v110, v111
	ds_read2_b64 v[2:5], v6 offset0:128 offset1:130
	ds_read2_b64 v[6:9], v6 offset0:132 offset1:134
	ds_read2_b64 v[10:13], v15 offset0:224 offset1:226
	v_exp_f32_e32 v0, v96
	v_cvt_pk_bf16_f32 v97, v194, v239
	v_cvt_pk_bf16_f32 v98, v100, v101
	v_cvt_pk_bf16_f32 v99, v102, v240
	v_cvt_pk_bf16_f32 v96, v0, v193
	v_max3_f32 v111, v80, v81, v82
	v_cvt_pk_bf16_f32 v242, v103, v104
	s_waitcnt lgkmcnt(2)
	v_mfma_f32_32x32x16_bf16 v[32:47], v[2:5], v[96:99], v[32:47]
	v_cvt_pk_bf16_f32 v243, v105, v106
	v_cvt_pk_bf16_f32 v244, v107, v108
	v_cvt_pk_bf16_f32 v245, v109, v110
	v_max3_f32 v192, v83, v84, v85
	v_max3_f32 v236, v86, v87, v88
	v_max3_f32 v237, v89, v90, v91
	v_max3_f32 v238, v92, v93, v94
	s_waitcnt lgkmcnt(0)
	v_mfma_f32_32x32x16_bf16 v[16:31], v[10:13], v[96:99], v[16:31]
	ds_read2_b64 v[96:99], v15 offset0:228 offset1:230
	v_max3_f32 v15, v111, v192, v95
	v_max3_f32 v236, v236, v237, v238
	v_mfma_f32_32x32x16_bf16 v[32:47], v[6:9], v[242:245], v[32:47]
	s_nop 1
	v_max_f32_e32 v15, v15, v236
	s_waitcnt lgkmcnt(0)
	v_mfma_f32_32x32x16_bf16 v[16:31], v[96:99], v[242:245], v[16:31]
	v_cmp_gt_f32_e32 vcc, v15, v213
	s_cbranch_vccz .LBB0_757
; DEV unsigned pack2(float a, float b) { f32x2 v = {a, b}; return __builtin_bit_cast(unsigned, __builtin_convertvector(v, bf2_t)); }
; DEV f32x16 mfma32(bf16x8 a, bf16x8 b, f32x16 c) { return __builtin_amdgcn_mfma_f32_32x32x16_bf16(a, b, c, 0, 0, 0); }
; DEV void attn_item(const Params& p, int item, char* smem) {
;     ...
;       if (__any(mx > mrun[jt])) {
;         const float mxa = fmaxf(mx, __shfl_xor(mx, 32));
;         const float mnew = fmaxf(mrun[jt], mxa);
;         const float alpha = __builtin_amdgcn_exp2f(mrun[jt] - mnew);
;         mrun[jt] = mnew;
;         lrun[jt] *= alpha;
; #pragma unroll
;         for (int dt = 0; dt < 2; dt++)
; #pragma unroll
;           for (int r = 0; r < 16; r++) o[dt][jt][r] *= alpha;
;       }
;       const float mcur = mrun[jt];
;       float pv[16];
; #pragma unroll
;       for (int r = 0; r < 16; r++) pv[r] = __builtin_amdgcn_exp2f(s[jt][r] - mcur);
;       lrun[jt] += (((pv[0] + pv[1]) + (pv[2] + pv[3])) + ((pv[4] + pv[5]) + (pv[6] + pv[7]))) +
;                   (((pv[8] + pv[9]) + (pv[10] + pv[11])) + ((pv[12] + pv[13]) + (pv[14] + pv[15])));
;       bf16x8 pf[2];
; #pragma unroll
;       for (int ss = 0; ss < 2; ss++) {
;         uint4 u; u.x = pack2(pv[8 * ss + 0], pv[8 * ss + 1]); u.y = pack2(pv[8 * ss + 2], pv[8 * ss + 3]);
;         u.z = pack2(pv[8 * ss + 4], pv[8 * ss + 5]); u.w = pack2(pv[8 * ss + 6], pv[8 * ss + 7]);
;         pf[ss] = __builtin_bit_cast(bf16x8, u);
;       }
; #pragma unroll
;       for (int dt = 0; dt < 2; dt++)
; #pragma unroll
;         for (int ss = 0; ss < 2; ss++) {
;           uint2 lo = *(const uint2*)(Vc + (dt * 32 + c31) * VSTR + 16 * ss + 4 * hf);
;           uint2 hi = *(const uint2*)(Vc + (dt * 32 + c31) * VSTR + 16 * ss + 8 + 4 * hf);
;           uint4 u; u.x = lo.x; u.y = lo.y; u.z = hi.x; u.w = hi.y;
;           o[dt][jt] = mfma32(__builtin_bit_cast(bf16x8, u), pf[ss], o[dt][jt]);
;         }
;     }
;     if (kt + 1 < ntile) {
;       bf16_t* Kn = Ks + ((kt + 1) & 1) * (32 * ASTR);
;       bf16_t* Vn = Vs + ((kt + 1) & 1) * (64 * VSTR);
;       *(u32x4*)(Kn + k0row * ASTR + k0cc * 8) = rk0;
;       if (has_k1) *(u32x4*)(Kn + k1row * ASTR + k1cc * 8) = rk1;
;       *(uint2*)(Vn + vrow * VSTR + vcc * 8) = make_uint2(rv0[0], rv0[1]);
;       *(uint2*)(Vn + vrow * VSTR + vcc * 8 + 4) = make_uint2(rv0[2], rv0[3]);
;       __syncthreads();
	v_mbcnt_hi_u32_b32 v111, -1, v215
	v_and_b32_e32 v236, 64, v111
	v_xor_b32_e32 v192, 32, v111
	v_add_u32_e32 v236, 64, v236
	v_cmp_lt_i32_e32 vcc, v192, v236
	s_nop 1
	v_cndmask_b32_e32 v111, v111, v192, vcc
	v_lshlrev_b32_e32 v111, 2, v111
	ds_bpermute_b32 v111, v111, v15
	s_waitcnt lgkmcnt(0)
	v_max_f32_e32 v111, v15, v111
	v_exp_f32_e64 v192, -v111
	v_add_f32_e32 v175, v175, v111
	v_mov_b32_e32 v213, 0x41000000
	v_sub_f32_e32 v80, v80, v111
	v_sub_f32_e32 v81, v81, v111
	v_sub_f32_e32 v82, v82, v111
	v_sub_f32_e32 v83, v83, v111
	v_sub_f32_e32 v84, v84, v111
	v_sub_f32_e32 v85, v85, v111
	v_sub_f32_e32 v86, v86, v111
	v_sub_f32_e32 v87, v87, v111
	v_sub_f32_e32 v88, v88, v111
	v_sub_f32_e32 v89, v89, v111
	v_sub_f32_e32 v90, v90, v111
	v_sub_f32_e32 v91, v91, v111
	v_sub_f32_e32 v92, v92, v111
	v_sub_f32_e32 v93, v93, v111
	v_sub_f32_e32 v94, v94, v111
	v_sub_f32_e32 v95, v95, v111
	v_sub_f32_e32 v220, v220, v111
	v_sub_f32_e32 v221, v221, v111
	v_sub_f32_e32 v222, v222, v111
	v_sub_f32_e32 v223, v223, v111
	v_sub_f32_e32 v224, v224, v111
	v_sub_f32_e32 v225, v225, v111
	v_sub_f32_e32 v226, v226, v111
	v_sub_f32_e32 v227, v227, v111
	v_sub_f32_e32 v228, v228, v111
	v_sub_f32_e32 v229, v229, v111
	v_sub_f32_e32 v230, v230, v111
	v_sub_f32_e32 v231, v231, v111
	v_sub_f32_e32 v232, v232, v111
	v_sub_f32_e32 v233, v233, v111
	v_sub_f32_e32 v234, v234, v111
	v_sub_f32_e32 v235, v235, v111
	v_mul_f32_e32 v184, v184, v192
	v_pk_mul_f32 v[78:79], v[78:79], v[192:193] op_sel_hi:[1,0]
	v_pk_mul_f32 v[76:77], v[76:77], v[192:193] op_sel_hi:[1,0]
	v_pk_mul_f32 v[74:75], v[74:75], v[192:193] op_sel_hi:[1,0]
	v_pk_mul_f32 v[72:73], v[72:73], v[192:193] op_sel_hi:[1,0]
	v_pk_mul_f32 v[70:71], v[70:71], v[192:193] op_sel_hi:[1,0]
	v_pk_mul_f32 v[68:69], v[68:69], v[192:193] op_sel_hi:[1,0]
	v_pk_mul_f32 v[66:67], v[66:67], v[192:193] op_sel_hi:[1,0]
	v_pk_mul_f32 v[64:65], v[64:65], v[192:193] op_sel_hi:[1,0]
	v_pk_mul_f32 v[62:63], v[62:63], v[192:193] op_sel_hi:[1,0]
	v_pk_mul_f32 v[60:61], v[60:61], v[192:193] op_sel_hi:[1,0]
	v_pk_mul_f32 v[58:59], v[58:59], v[192:193] op_sel_hi:[1,0]
	v_pk_mul_f32 v[56:57], v[56:57], v[192:193] op_sel_hi:[1,0]
	v_pk_mul_f32 v[54:55], v[54:55], v[192:193] op_sel_hi:[1,0]
	v_pk_mul_f32 v[52:53], v[52:53], v[192:193] op_sel_hi:[1,0]
	v_pk_mul_f32 v[50:51], v[50:51], v[192:193] op_sel_hi:[1,0]
	v_pk_mul_f32 v[48:49], v[48:49], v[192:193] op_sel_hi:[1,0]
.LBB0_757:
	v_exp_f32_e32 v80, v80
	v_exp_f32_e32 v81, v81
	v_exp_f32_e32 v82, v82
	v_exp_f32_e32 v83, v83
	v_exp_f32_e32 v84, v84
	v_exp_f32_e32 v85, v85
	v_exp_f32_e32 v86, v86
	v_exp_f32_e32 v111, v87
	v_exp_f32_e32 v87, v88
	v_exp_f32_e32 v88, v89
	v_exp_f32_e32 v89, v90
	v_cvt_pk_bf16_f32 v242, v80, v81
	v_cvt_pk_bf16_f32 v243, v82, v83
	v_cvt_pk_bf16_f32 v244, v84, v85
	v_cvt_pk_bf16_f32 v245, v86, v111
	v_exp_f32_e32 v90, v91
	v_exp_f32_e32 v91, v92
	v_mfma_f32_32x32x16_bf16 v[64:79], v[2:5], v[242:245], v[64:79]
	v_exp_f32_e32 v92, v93
	v_exp_f32_e32 v2, v94
	v_exp_f32_e32 v3, v95
	v_mfma_f32_32x32x16_bf16 v[48:63], v[10:13], v[242:245], v[48:63]
	v_cvt_pk_bf16_f32 v246, v87, v88
	v_cvt_pk_bf16_f32 v247, v89, v90
	v_cvt_pk_bf16_f32 v248, v91, v92
	v_cvt_pk_bf16_f32 v249, v2, v3
	s_add_i32 s12, s12, 1
	s_and_b32 s14, s12, 1
	s_mul_i32 s15, s14, 0x1a00
	v_mfma_f32_32x32x16_bf16 v[64:79], v[6:9], v[246:249], v[64:79]
	v_lshlrev_b32_e32 v15, 1, v191
	v_lshlrev_b32_e32 v192, 1, v176
	v_add3_u32 v4, s15, v15, v192
	s_waitcnt vmcnt(0)
	ds_write_b128 v4, v[168:171]
	v_mfma_f32_32x32x16_bf16 v[48:63], v[96:99], v[246:249], v[48:63]
	s_and_saveexec_b64 s[8:9], s[38:39]
	s_cbranch_execz .LBB0_752
	v_lshlrev_b32_e32 v4, 1, v174
	v_add3_u32 v4, s15, v188, v4
	ds_write_b128 v4, v[164:167]
	s_branch .LBB0_752
.LBB0_759:
	v_mov_b32_e32 v226, -12
	v_add_u32_e32 v0, s15, v187
	ds_read_b128 v[2:5], v0
	ds_read_b128 v[6:9], v0 offset:32
	ds_read_b128 v[10:13], v0 offset:64
	ds_read_b128 v[178:181], v0 offset:96
	ds_read_b128 v[240:243], v0 offset:128
	ds_read_b128 v[244:247], v0 offset:160
	s_mov_b64 s[34:35], 0x100
	s_waitcnt lgkmcnt(5)
	v_mfma_f32_32x32x16_bf16 v[96:111], v[2:5], v[156:159], 0
	s_waitcnt lgkmcnt(4)
	v_mfma_f32_32x32x16_bf16 v[96:111], v[6:9], v[152:155], v[96:111]
	v_mfma_f32_32x32x16_bf16 v[80:95], v[2:5], v[132:135], 0
	s_waitcnt lgkmcnt(3)
	v_mfma_f32_32x32x16_bf16 v[96:111], v[10:13], v[148:151], v[96:111]
	v_mfma_f32_32x32x16_bf16 v[80:95], v[6:9], v[128:131], v[80:95]
	s_waitcnt lgkmcnt(2)
	v_mfma_f32_32x32x16_bf16 v[96:111], v[178:181], v[144:147], v[96:111]
	v_mfma_f32_32x32x16_bf16 v[80:95], v[10:13], v[112:115], v[80:95]
	s_waitcnt lgkmcnt(1)
	v_mfma_f32_32x32x16_bf16 v[96:111], v[240:243], v[140:143], v[96:111]
	v_mfma_f32_32x32x16_bf16 v[80:95], v[178:181], v[116:119], v[80:95]
	s_waitcnt lgkmcnt(0)
	v_mfma_f32_32x32x16_bf16 v[96:111], v[244:247], v[136:139], v[96:111]
	v_mfma_f32_32x32x16_bf16 v[80:95], v[240:243], v[120:123], v[80:95]
	s_nop 10
	v_max_f32_e32 v0, v99, v99
	v_max_f32_e32 v2, v98, v98
	v_max_f32_e32 v0, v2, v0
	v_max_f32_e32 v2, v103, v103
	v_max_f32_e32 v3, v102, v102
	v_max_f32_e32 v2, v3, v2
	v_max_f32_e32 v3, v105, v105
	v_max_f32_e32 v4, v104, v104
	v_mfma_f32_32x32x16_bf16 v[80:95], v[244:247], v[124:127], v[80:95]
	v_max_f32_e32 v3, v4, v3
	v_max_f32_e32 v4, v107, v107
	v_max_f32_e32 v5, v106, v106
	v_max_f32_e32 v4, v5, v4
	v_max_f32_e32 v5, v111, v111
	v_max_f32_e32 v6, v110, v110
	v_max_f32_e32 v5, v6, v5
	v_max3_f32 v5, v108, v109, v5
	v_max3_f32 v0, v96, v97, v0
	v_max3_f32 v2, v100, v101, v2
	v_max3_f32 v3, v3, v4, v5
	v_max3_f32 v0, v0, v2, v3
	v_cmp_gt_f32_e32 vcc, v0, v185
	s_cbranch_vccz .LBB0_761
	v_mbcnt_hi_u32_b32 v2, -1, v215
	v_and_b32_e32 v4, 64, v2
	v_xor_b32_e32 v3, 32, v2
	v_add_u32_e32 v4, 64, v4
	v_cmp_lt_i32_e32 vcc, v3, v4
	s_nop 1
	v_cndmask_b32_e32 v2, v2, v3, vcc
	v_lshlrev_b32_e32 v2, 2, v2
	ds_bpermute_b32 v2, v2, v0
	s_waitcnt lgkmcnt(0)
	v_max3_f32 v2, v185, v0, v2
	v_sub_f32_e32 v0, v185, v2
	v_exp_f32_e32 v0, v0
	v_mov_b32_e32 v185, v2
	v_mul_f32_e32 v14, v14, v0
	v_pk_mul_f32 v[46:47], v[46:47], v[0:1] op_sel_hi:[1,0]
	v_pk_mul_f32 v[44:45], v[44:45], v[0:1] op_sel_hi:[1,0]
	v_pk_mul_f32 v[42:43], v[42:43], v[0:1] op_sel_hi:[1,0]
	v_pk_mul_f32 v[40:41], v[40:41], v[0:1] op_sel_hi:[1,0]
	v_pk_mul_f32 v[38:39], v[38:39], v[0:1] op_sel_hi:[1,0]
	v_pk_mul_f32 v[36:37], v[36:37], v[0:1] op_sel_hi:[1,0]
	v_pk_mul_f32 v[34:35], v[34:35], v[0:1] op_sel_hi:[1,0]
	v_pk_mul_f32 v[32:33], v[32:33], v[0:1] op_sel_hi:[1,0]
	v_pk_mul_f32 v[30:31], v[30:31], v[0:1] op_sel_hi:[1,0]
	v_pk_mul_f32 v[28:29], v[28:29], v[0:1] op_sel_hi:[1,0]
	v_pk_mul_f32 v[26:27], v[26:27], v[0:1] op_sel_hi:[1,0]
	v_pk_mul_f32 v[24:25], v[24:25], v[0:1] op_sel_hi:[1,0]
	v_pk_mul_f32 v[22:23], v[22:23], v[0:1] op_sel_hi:[1,0]
	v_pk_mul_f32 v[20:21], v[20:21], v[0:1] op_sel_hi:[1,0]
	v_pk_mul_f32 v[18:19], v[18:19], v[0:1] op_sel_hi:[1,0]
	v_pk_mul_f32 v[16:17], v[16:17], v[0:1] op_sel_hi:[1,0]

; __global__ void __launch_bounds__(256, 2) fwd_megakernel(Params p) {
;     ...
; #pragma unroll 1
;   for (int ph = 0; ph < NPHASE; ph++) {
;     if (ph == 11) continue;
;     if (ph == 10 || ph == 20) { run_phase(ph + 100, smem); xcd_barrier(xb); }
;     run_phase(ph, smem);
;     if (ph + 1 < NPHASE) xcd_barrier(xb);
;     if (p.ws == nullptr) grid.sync();
;   }
.LBB0_770:
	v_mov_b32_e32 v196, 0x3ba10414
	v_mov_b32_e32 v197, 0x13c00
	v_mov_b32_e32 v198, 0x13c04
	v_mov_b32_e32 v199, 1
	v_mov_b32_e32 v200, 0x13b40
	v_mov_b32_e32 v201, 0x13b50
	v_mov_b32_e32 v202, 0x13b60
	v_mov_b32_e32 v203, 0x13b70
	v_mov_b32_e32 v204, 0x13b80
	v_mov_b32_e32 v205, 0x13b90
	v_mov_b32_e32 v206, 0x13ba0
	v_mov_b32_e32 v207, 0x13bb0
	v_mov_b32_e32 v208, 0x13bc0
	v_mov_b32_e32 v209, 0x13bd0
	v_mov_b32_e32 v210, 0x13be0
	v_mov_b32_e32 v211, 0x358637bd
	v_mov_b32_e32 v212, 0x8300000
	v_mov_b32_e32 v213, 0x7fc00000
	v_mov_b32_e32 v222, 0xb9c68948
	v_mov_b32_e32 v223, 0x7f800000
	v_mov_b32_e32 v224, 0xe300000
	v_mov_b32_e32 v225, 0x41b17218
	v_mov_b32_e32 v226, -12
	v_mov_b32_e32 v227, 0x9800
	v_mov_b32_e32 v228, 0x6700000
	v_mov_b32_e32 v229, 0xc300000
	v_xor_b32_e32 v220, 4, v216
	v_xor_b32_e32 v221, 8, v216
	v_not_b32_e32 v230, 63
	v_not_b32_e32 v231, 31
	v_readlane_b32 s30, v253, 11
	v_readlane_b32 s28, v254, 0
	v_readlane_b32 s31, v253, 12
	s_movk_i32 s19, 0x880
	s_movk_i32 s23, 0x3fff
	s_movk_i32 s21, 0x2000
	v_readlane_b32 s29, v254, 1
